# barrier pollers sleep longer between polls (less polling traffic during tail rounds)
# speedup vs baseline: 1.0251x; 1.0026x over previous
.Lgb_poll_2:
	global_load_dword v1, v0, s[100:101] offset:128 sc1
	s_waitcnt vmcnt(0)
	v_cmp_le_u32_e32 vcc, s98, v1
	s_cbranch_vccnz .Lgb_done_2
	s_sleep 6
	s_branch .Lgb_poll_2
